# Strategy: waits to first consumer (docs 7.2) in the S5 chunk loop - the skip-term ushort loads land in private registers and are packed one iteration later, right before the C-projection block that us
# speedup vs baseline: 1.0053x; 1.0034x over previous
.LBB0_1091:
	s_add_i32 s40, s40, 1
	s_add_i32 s2, s2, 64
	v_lshl_add_u64 v[120:121], v[120:121], 0, s[34:35]
	s_waitcnt lgkmcnt(0)
	s_barrier
	s_and_b64 vcc, exec, s[28:29]
	s_cbranch_vccz .Ls5T_done_0
	s_cmp_eq_u32 s100, 0
	s_cbranch_scc1 .Ls5T_noperm_0
	s_waitcnt vmcnt(8)
	s_mov_b32 s94, 1
	s_branch .Ls5T_mov_0
.Ls5T_noperm_0:
	s_mov_b32 s94, 0
	s_cmp_eq_u32 s71, 0
	s_cbranch_scc1 .Ls5T_w0_0
	s_cmp_eq_u32 s71, 2
	s_cbranch_scc1 .Ls5T_w4_0
	s_waitcnt vmcnt(7)
	s_branch .Ls5T_mov_0

.LBB0_1103:
	s_cmpk_eq_i32 s2, 0xffc0
	s_cbranch_scc1 .LBB0_1106
	s_andn2_b64 vcc, exec, s[24:25]
	s_cbranch_vccnz .LBB0_1106
	s_cmp_eq_u32 s94, 0
	s_cbranch_scc1 .Ls5uun_skip_0
	s_cmpk_eq_i32 s2, 0xf80
	s_cbranch_scc1 .Ls5uun_all_0
	s_waitcnt vmcnt(1)
	s_branch .Ls5uun_pack_0

.Ls5uun_pack_0:
	v_perm_b32 v143, v165, v164, s51
	v_perm_b32 v107, v167, v166, s51
.Ls5uun_skip_0:
	s_and_b32 s38, s2, 64
	s_mulk_i32 s38, 0x110
	v_add_u32_e32 v66, s38, v125
	ds_read_b128 v[8:11], v66
	ds_read_b128 v[12:15], v66 offset:64
	ds_read_b128 v[148:151], v66 offset:128
	ds_read_b128 v[152:155], v66 offset:192
	v_lshlrev_b32_e32 v66, 16, v143
	s_waitcnt lgkmcnt(3)
	v_mfma_f32_16x16x32_bf16 v[8:11], v[8:11], v[48:51], 0
	v_and_b32_e32 v143, 0xffff0000, v143
	v_lshlrev_b32_e32 v147, 16, v107
	v_lshl_add_u64 v[156:157], v[116:117], 0, s[2:3]
	s_waitcnt lgkmcnt(2)
	v_mfma_f32_16x16x32_bf16 v[8:11], v[12:15], v[44:47], v[8:11]
	v_lshlrev_b64 v[12:13], 10, v[156:157]
	v_lshl_add_u64 v[14:15], v[110:111], 0, v[12:13]
	s_waitcnt lgkmcnt(1)
	v_mfma_f32_16x16x32_bf16 v[8:11], v[148:151], v[40:43], v[8:11]
	v_or_b32_e32 v148, 0x400, v12
	v_mov_b32_e32 v149, v13
	s_waitcnt lgkmcnt(0)
	v_mfma_f32_16x16x32_bf16 v[8:11], v[152:155], v[36:39], v[8:11]
	s_nop 7
	v_fma_f32 v8, v142, v66, v8
	v_mul_f32_e32 v66, 0x3d372713, v8
	v_fma_f32 v9, v142, v143, v9
	v_mul_f32_e32 v66, v8, v66
	v_mul_f32_e32 v143, 0x3d372713, v9
	v_fma_f32 v66, v8, v66, v8
	v_mul_f32_e32 v143, v9, v143
	v_mul_f32_e32 v66, 0xbfcc422a, v66
	v_fma_f32 v143, v9, v143, v9
	v_mul_f32_e32 v66, 0x3fb8aa3b, v66
	v_mul_f32_e32 v143, 0xbfcc422a, v143
	v_exp_f32_e32 v66, v66
	v_mul_f32_e32 v143, 0x3fb8aa3b, v143
	v_exp_f32_e32 v143, v143
	v_fma_f32 v10, v142, v147, v10
	v_add_f32_e32 v66, 1.0, v66
	v_rcp_f32_e32 v66, v66
	v_add_f32_e32 v143, 1.0, v143
	v_mul_f32_e32 v147, 0x3d372713, v10
	v_rcp_f32_e32 v143, v143
	v_mul_f32_e32 v147, v10, v147
	v_fma_f32 v147, v10, v147, v10
	v_mul_f32_e32 v8, v8, v66
	v_mul_f32_e32 v147, 0xbfcc422a, v147
	v_cvt_pk_bf16_f32 v8, v8, s0
	v_mul_f32_e32 v9, v9, v143
	global_store_short v[14:15], v8, off
	v_mul_f32_e32 v8, 0x3fb8aa3b, v147
	v_cvt_pk_bf16_f32 v66, v9, s0
	v_exp_f32_e32 v14, v8
	v_lshl_add_u64 v[8:9], v[110:111], 0, v[148:149]
	global_store_short v[8:9], v66, off
	v_and_b32_e32 v9, 0xffff0000, v107
	v_fmac_f32_e32 v11, v142, v9
	v_mul_f32_e32 v9, 0x3d372713, v11
	v_mul_f32_e32 v9, v11, v9
	v_fma_f32 v9, v11, v9, v11
	v_mul_f32_e32 v9, 0xbfcc422a, v9
	v_mul_f32_e32 v9, 0x3fb8aa3b, v9
	v_exp_f32_e32 v9, v9
	v_add_f32_e32 v8, 1.0, v14
	v_rcp_f32_e32 v8, v8
	v_add_f32_e32 v9, 1.0, v9
	v_rcp_f32_e32 v14, v9
	v_mul_f32_e32 v8, v10, v8
	v_cvt_pk_bf16_f32 v10, v8, s0
	v_or_b32_e32 v8, 0x800, v12
	v_mov_b32_e32 v9, v13
	v_lshl_add_u64 v[8:9], v[110:111], 0, v[8:9]
	global_store_short v[8:9], v10, off
	v_mul_f32_e32 v8, v11, v14
	v_or_b32_e32 v12, 0xc00, v12
	v_cvt_pk_bf16_f32 v10, v8, s0
	v_lshl_add_u64 v[8:9], v[110:111], 0, v[12:13]
	global_store_short v[8:9], v10, off
	v_lshl_add_u64 v[8:9], v[120:121], 0, s[30:31]
	v_or_b32_e32 v12, 0x1000, v8
	v_mov_b32_e32 v13, v9
	v_or_b32_e32 v14, 0x2000, v8
	v_or_b32_e32 v8, 0x3000, v8
	v_lshl_add_u64 v[10:11], v[112:113], 0, v[120:121]
	v_lshl_add_u64 v[12:13], v[118:119], 0, v[12:13]
	v_mov_b32_e32 v15, v9
	v_lshl_add_u64 v[8:9], v[118:119], 0, v[8:9]
	v_lshl_add_u64 v[14:15], v[118:119], 0, v[14:15]
	global_load_ushort v164, v[10:11], off
	s_nop 0
	global_load_ushort v165, v[12:13], off
	s_nop 0
	global_load_ushort v166, v[14:15], off
	s_nop 0
	global_load_ushort v167, v[8:9], off
	s_mov_b32 s100, 1

.LBB0_1109:
	s_andn2_b64 vcc, exec, s[26:27]
	s_cbranch_vccnz .LBB0_1050
	s_waitcnt vmcnt(0)
	v_perm_b32 v143, v165, v164, s51
	v_perm_b32 v107, v167, v166, s51
	ds_read_b128 v[0:3], v133
	ds_read_b128 v[4:7], v133 offset:64
	ds_read_b128 v[8:11], v133 offset:128
	ds_read_b128 v[12:15], v133 offset:192
	s_waitcnt lgkmcnt(3)
	v_mfma_f32_16x16x32_bf16 v[0:3], v[0:3], v[48:51], 0
	v_mov_b32_e32 v49, s37
	v_or_b32_e32 v48, s36, v88
	s_waitcnt lgkmcnt(2)
	v_mfma_f32_16x16x32_bf16 v[0:3], v[4:7], v[44:47], v[0:3]
	v_lshlrev_b32_e32 v44, 16, v143
	v_and_b32_e32 v45, 0xffff0000, v143
	v_lshlrev_b32_e32 v46, 16, v107
	s_waitcnt lgkmcnt(1)
	v_mfma_f32_16x16x32_bf16 v[0:3], v[8:11], v[40:43], v[0:3]
	v_lshlrev_b64 v[4:5], 10, v[48:49]
	v_lshl_add_u64 v[6:7], v[110:111], 0, v[4:5]
	v_or_b32_e32 v8, 0x400, v4
	s_waitcnt lgkmcnt(0)
	v_mfma_f32_16x16x32_bf16 v[0:3], v[12:15], v[36:39], v[0:3]
	s_nop 7
	v_fma_f32 v0, v142, v44, v0
	v_mul_f32_e32 v9, 0x3d372713, v0
	v_mul_f32_e32 v9, v0, v9
	v_fma_f32 v1, v142, v45, v1
	v_fma_f32 v9, v0, v9, v0
	v_mul_f32_e32 v10, 0x3d372713, v1
	v_mul_f32_e32 v9, 0xbfcc422a, v9
	v_mul_f32_e32 v10, v1, v10
	v_mul_f32_e32 v9, 0x3fb8aa3b, v9
	v_fma_f32 v10, v1, v10, v1
	v_exp_f32_e32 v9, v9
	v_mul_f32_e32 v10, 0xbfcc422a, v10
	v_mul_f32_e32 v10, 0x3fb8aa3b, v10
	v_exp_f32_e32 v10, v10
	v_add_f32_e32 v9, 1.0, v9
	v_rcp_f32_e32 v9, v9
	v_fma_f32 v2, v142, v46, v2
	v_add_f32_e32 v10, 1.0, v10
	v_mul_f32_e32 v11, 0x3d372713, v2
	v_rcp_f32_e32 v10, v10
	v_mul_f32_e32 v11, v2, v11
	v_mul_f32_e32 v0, v0, v9
	v_fma_f32 v11, v2, v11, v2
	v_cvt_pk_bf16_f32 v0, v0, s0
	global_store_short v[6:7], v0, off
	v_mul_f32_e32 v0, 0xbfcc422a, v11
	v_mul_f32_e32 v1, v1, v10
	v_mul_f32_e32 v0, 0x3fb8aa3b, v0
	v_mov_b32_e32 v9, v5
	v_cvt_pk_bf16_f32 v10, v1, s0
	v_exp_f32_e32 v6, v0
	v_lshl_add_u64 v[0:1], v[110:111], 0, v[8:9]
	global_store_short v[0:1], v10, off
	v_and_b32_e32 v1, 0xffff0000, v107
	v_fmac_f32_e32 v3, v142, v1
	v_mul_f32_e32 v1, 0x3d372713, v3
	v_mul_f32_e32 v1, v3, v1
	v_fma_f32 v1, v3, v1, v3
	v_mul_f32_e32 v1, 0xbfcc422a, v1
	v_mul_f32_e32 v1, 0x3fb8aa3b, v1
	v_exp_f32_e32 v1, v1
	v_add_f32_e32 v0, 1.0, v6
	v_rcp_f32_e32 v0, v0
	v_add_f32_e32 v1, 1.0, v1
	v_rcp_f32_e32 v6, v1
	v_mul_f32_e32 v0, v2, v0
	v_cvt_pk_bf16_f32 v2, v0, s0
	v_or_b32_e32 v0, 0x800, v4
	v_mov_b32_e32 v1, v5
	v_lshl_add_u64 v[0:1], v[110:111], 0, v[0:1]
	global_store_short v[0:1], v2, off
	v_mul_f32_e32 v0, v3, v6
	v_or_b32_e32 v4, 0xc00, v4
	v_cvt_pk_bf16_f32 v2, v0, s0
	v_lshl_add_u64 v[0:1], v[110:111], 0, v[4:5]
	global_store_short v[0:1], v2, off
	s_branch .LBB0_1050
